# conv_p (runs beside K_A's last GEMM round): four source loads per pass issued together with a branch-free source select; it was one load / wait / store per element and outlasted the GEMM round
# baseline (speedup 1.0000x reference)
; __device__ __forceinline__ int tid_() { int t = (int)threadIdx.x; asm volatile("" : "+v"(t)); return t & 511; }
; __device__ __forceinline__ int bid_() { int b = (int)blockIdx.x; asm volatile("" : "+s"(b)); return b; }
; __device__ __forceinline__ int gdim_() { int g = (int)gridDim.x; asm volatile("" : "+s"(g)); return g; }
; DI unsigned pk2(float lo, float hi) { const f32x2v v = {lo, hi}; const bf16x2v b = __builtin_convertvector(v, bf16x2v); return __builtin_bit_cast(unsigned, b); }
; DI void conv_p(const Params& P, int l) {
;     const int gt = bid_() * 512 + tid_(), NT = gdim_() * 512; bf16_t* PB = (bf16_t*)(P.ws + O_PBF);
; #pragma unroll 4
;     for (int i = gt; i < T * 64; i += NT) { const int row = i >> 6, c4 = (i & 63) * 4;
;         const float* src = row < TP ? P.in[I_PP] + ((size_t)l * TP + row) * 256 + c4 : P.in[I_PS] + ((size_t)l * 512 + (row - TP)) * 256 + c4;
;         const f32x4 v = *(const f32x4*)src; u32x2 w; w.x = pk2(v[0], v[1]); w.y = pk2(v[2], v[3]); *(u32x2*)(PB + (size_t)row * 256 + c4) = w; }
.LBB0_902:
	s_or_b64 exec, exec, s[10:11]
	v_cndmask_b32_e64 v0, 0, 1, vcc
	v_add_u32_e32 v0, v1, v0
	v_cmp_lt_u32_e32 vcc, 2, v0
	s_and_b64 exec, exec, vcc
	s_cbranch_execz .LBB0_921
	v_lshlrev_b32_e32 v1, 2, v8
	s_lshl_b32 s14, s17, 13
	s_mov_b64 s[10:11], 0
	s_load_dwordx2 s[20:21], s[4:5], 0x38
	s_load_dwordx2 s[22:23], s[4:5], 0x30
	s_waitcnt lgkmcnt(0)
	s_branch .LBB0_905
.LBB0_905:
	v_and_b32_e32 v0, 0xfc, v1
	v_lshlrev_b32_e32 v2, 2, v0
	v_mov_b32_e32 v3, v25
	v_lshlrev_b32_e32 v24, 1, v0
	v_ashrrev_i32_e32 v30, 6, v8
	v_ashrrev_i32_e32 v31, 31, v30
	v_cmp_lt_i32_e32 vcc, s94, v30
	v_lshl_add_u64 v[38:39], v[30:31], 0, s[36:37]
	v_lshlrev_b64 v[38:39], 10, v[38:39]
	v_lshl_add_u64 v[38:39], s[22:23], 0, v[38:39]
	v_add_u32_e32 v54, s3, v30
	v_add_u32_e32 v54, 0xffffc000, v54
	v_mov_b32_e32 v55, 0
	v_lshlrev_b64 v[46:47], 10, v[54:55]
	v_lshl_add_u64 v[46:47], s[20:21], 0, v[46:47]
	v_cndmask_b32_e32 v38, v38, v46, vcc
	v_cndmask_b32_e32 v39, v39, v47, vcc
	v_lshl_add_u64 v[38:39], v[38:39], 0, v[2:3]
	global_load_dwordx4 v[62:65], v[38:39], off
	v_lshlrev_b64 v[78:79], 9, v[30:31]
	v_lshl_add_u64 v[78:79], s[8:9], 0, v[78:79]
	v_lshl_add_u64 v[78:79], v[78:79], 0, v[24:25]
	v_add_u32_e32 v8, s2, v8
	v_ashrrev_i32_e32 v32, 6, v8
	v_ashrrev_i32_e32 v33, 31, v32
	v_cmp_lt_i32_e32 vcc, s94, v32
	v_lshl_add_u64 v[40:41], v[32:33], 0, s[36:37]
	v_lshlrev_b64 v[40:41], 10, v[40:41]
	v_lshl_add_u64 v[40:41], s[22:23], 0, v[40:41]
	v_add_u32_e32 v56, s3, v32
	v_add_u32_e32 v56, 0xffffc000, v56
	v_mov_b32_e32 v57, 0
	v_lshlrev_b64 v[48:49], 10, v[56:57]
	v_lshl_add_u64 v[48:49], s[20:21], 0, v[48:49]
	v_cndmask_b32_e32 v40, v40, v48, vcc
	v_cndmask_b32_e32 v41, v41, v49, vcc
	v_lshl_add_u64 v[40:41], v[40:41], 0, v[2:3]
	global_load_dwordx4 v[66:69], v[40:41], off
	v_lshlrev_b64 v[80:81], 9, v[32:33]
	v_lshl_add_u64 v[80:81], s[8:9], 0, v[80:81]
	v_lshl_add_u64 v[80:81], v[80:81], 0, v[24:25]
	v_add_u32_e32 v8, s2, v8
	v_ashrrev_i32_e32 v34, 6, v8
	v_ashrrev_i32_e32 v35, 31, v34
	v_cmp_lt_i32_e32 vcc, s94, v34
	v_lshl_add_u64 v[42:43], v[34:35], 0, s[36:37]
	v_lshlrev_b64 v[42:43], 10, v[42:43]
	v_lshl_add_u64 v[42:43], s[22:23], 0, v[42:43]
	v_add_u32_e32 v58, s3, v34
	v_add_u32_e32 v58, 0xffffc000, v58
	v_mov_b32_e32 v59, 0
	v_lshlrev_b64 v[50:51], 10, v[58:59]
	v_lshl_add_u64 v[50:51], s[20:21], 0, v[50:51]
	v_cndmask_b32_e32 v42, v42, v50, vcc
	v_cndmask_b32_e32 v43, v43, v51, vcc
	v_lshl_add_u64 v[42:43], v[42:43], 0, v[2:3]
	global_load_dwordx4 v[70:73], v[42:43], off
	v_lshlrev_b64 v[82:83], 9, v[34:35]
	v_lshl_add_u64 v[82:83], s[8:9], 0, v[82:83]
	v_lshl_add_u64 v[82:83], v[82:83], 0, v[24:25]
	v_add_u32_e32 v8, s2, v8
	v_ashrrev_i32_e32 v36, 6, v8
	v_ashrrev_i32_e32 v37, 31, v36
	v_cmp_lt_i32_e32 vcc, s94, v36
	v_lshl_add_u64 v[44:45], v[36:37], 0, s[36:37]
	v_lshlrev_b64 v[44:45], 10, v[44:45]
	v_lshl_add_u64 v[44:45], s[22:23], 0, v[44:45]
	v_add_u32_e32 v60, s3, v36
	v_add_u32_e32 v60, 0xffffc000, v60
	v_mov_b32_e32 v61, 0
	v_lshlrev_b64 v[52:53], 10, v[60:61]
	v_lshl_add_u64 v[52:53], s[20:21], 0, v[52:53]
	v_cndmask_b32_e32 v44, v44, v52, vcc
	v_cndmask_b32_e32 v45, v45, v53, vcc
	v_lshl_add_u64 v[44:45], v[44:45], 0, v[2:3]
	global_load_dwordx4 v[74:77], v[44:45], off
	v_lshlrev_b64 v[84:85], 9, v[36:37]
	v_lshl_add_u64 v[84:85], s[8:9], 0, v[84:85]
	v_lshl_add_u64 v[84:85], v[84:85], 0, v[24:25]
	v_add_u32_e32 v8, s2, v8
	s_mov_b32 s12, 0x107fff
	v_cmp_lt_i32_e32 vcc, s12, v8
	s_or_b64 s[10:11], vcc, s[10:11]
	v_add_u32_e32 v1, s14, v1
	s_waitcnt vmcnt(0)
	v_cvt_pk_bf16_f32 v62, v62, v63
	v_cvt_pk_bf16_f32 v63, v64, v65
	global_store_dwordx2 v[78:79], v[62:63], off
	v_cvt_pk_bf16_f32 v66, v66, v67
	v_cvt_pk_bf16_f32 v67, v68, v69
	global_store_dwordx2 v[80:81], v[66:67], off
	v_cvt_pk_bf16_f32 v70, v70, v71
	v_cvt_pk_bf16_f32 v71, v72, v73
	global_store_dwordx2 v[82:83], v[70:71], off
	v_cvt_pk_bf16_f32 v74, v74, v75
	v_cvt_pk_bf16_f32 v75, v76, v77
	global_store_dwordx2 v[84:85], v[74:75], off
	s_andn2_b64 exec, exec, s[10:11]
	s_cbranch_execnz .LBB0_905
